# selection walk QK: counted lgkmcnt waits per K fragment (wait at first consumer)
# baseline (speedup 1.0000x reference)
.LBB0_1260:
	s_cmp_lt_i32 s21, 0
	s_cbranch_scc1 .LBB0_1254
	s_lshl_b32 s23, 1, s21
	s_cmpk_lt_u32 s21, 0x60
	s_cselect_b64 s[4:5], -1, 0
	s_and_b64 s[6:7], s[4:5], exec
	s_cselect_b32 s25, s50, s52
	s_cselect_b32 s26, s51, s53
	s_cmp_lt_u32 s21, 64
	s_cselect_b64 s[6:7], -1, 0
	s_and_b64 s[8:9], s[6:7], exec
	s_cselect_b32 s25, s46, s25
	s_cselect_b32 s42, s47, s26
	s_cmp_lt_u32 s21, 32
	s_cselect_b64 s[8:9], -1, 0
	s_and_b64 s[26:27], s[8:9], exec
	s_cselect_b32 s26, s44, s25
	s_cselect_b32 s25, s45, s42
	s_or_b32 s27, s26, s25
	s_and_b32 s27, s27, s23
	s_cmp_eq_u32 s27, 0
	s_cbranch_scc1 .LBB0_1276
	s_waitcnt lgkmcnt(0)
	v_add_u32_e32 v0, s15, v198
	v_add_u32_e32 v1, s15, v197
	ds_read_b128 v[98:101], v0
	ds_read_b128 v[102:105], v0 offset:2048
	ds_read_b128 v[118:121], v1
	ds_read_b128 v[110:113], v1 offset:2048
	ds_read_b128 v[114:117], v0 offset:4096
	ds_read_b128 v[94:97], v0 offset:6144
	ds_read_b128 v[106:109], v1 offset:4096
	ds_read_b128 v[90:93], v1 offset:6144
	s_and_b32 s42, s26, s23
	s_cmp_lg_u32 s42, 0
	s_cselect_b64 s[26:27], -1, 0
	s_cmp_eq_u32 s42, 0
	s_cbranch_scc1 .LBB0_1267
	s_waitcnt lgkmcnt(7)
	v_mfma_f32_16x16x32_bf16 v[0:3], v[98:101], v[22:25], 0
	v_cndmask_b32_e64 v4, v21, v20, s[4:5]
	v_cndmask_b32_e64 v4, v4, v19, s[6:7]
	v_cndmask_b32_e64 v4, v4, v18, s[8:9]
	s_waitcnt lgkmcnt(5)
	v_mfma_f32_16x16x32_bf16 v[126:129], v[118:121], v[26:29], v[0:3]
	v_and_b32_e32 v4, s23, v4
	s_lshl_b32 s42, s21, 6
	v_subrev_u32_e32 v5, s42, v132
	v_mfma_f32_16x16x32_bf16 v[0:3], v[102:105], v[22:25], 0
	v_cmp_ne_u32_e32 vcc, 0, v4
	s_waitcnt lgkmcnt(4)
	v_mfma_f32_16x16x32_bf16 v[82:85], v[110:113], v[26:29], v[0:3]
	s_nop 0
	v_cndmask_b32_e32 v199, -1, v5, vcc
	v_cmp_gt_u32_e32 vcc, 63, v199
	s_waitcnt lgkmcnt(3)
	v_mfma_f32_16x16x32_bf16 v[0:3], v[114:117], v[22:25], 0
	s_waitcnt lgkmcnt(1)
	v_mfma_f32_16x16x32_bf16 v[74:77], v[106:109], v[26:29], v[0:3]
	v_mfma_f32_16x16x32_bf16 v[0:3], v[94:97], v[22:25], 0
	s_waitcnt lgkmcnt(0)
	v_mfma_f32_16x16x32_bf16 v[122:125], v[90:93], v[26:29], v[0:3]
	s_cbranch_vccz .LBB0_1277
	v_cmp_le_i32_e32 vcc, v153, v199
	s_nop 4
	v_cndmask_b32_e32 v0, v246, v126, vcc
	v_cmp_lt_i32_e32 vcc, v153, v199
	s_nop 1
	v_cndmask_b32_e32 v1, v246, v127, vcc
	v_cmp_le_i32_e32 vcc, v155, v199
	v_max3_f32 v4, v0, s96, v1
	s_nop 0
	v_cndmask_b32_e32 v2, v246, v128, vcc
	v_cmp_le_i32_e32 vcc, v156, v199
	s_nop 1
	v_cndmask_b32_e32 v3, v246, v129, vcc
	v_cmp_le_i32_e32 vcc, v158, v199
	v_max3_f32 v6, v4, v2, v3
	s_nop 0
	v_cndmask_b32_e32 v4, v246, v82, vcc
	v_cmp_le_i32_e32 vcc, v159, v199
	s_nop 1
	v_cndmask_b32_e32 v5, v246, v83, vcc
	v_cmp_le_i32_e32 vcc, v160, v199
	v_max3_f32 v8, v6, v4, v5
	s_nop 0
	v_cndmask_b32_e32 v6, v246, v84, vcc
	v_cmp_le_i32_e32 vcc, v161, v199
	s_nop 1
	v_cndmask_b32_e32 v7, v246, v85, vcc
	v_cmp_le_i32_e32 vcc, v162, v199
	v_max3_f32 v10, v8, v6, v7
	s_nop 0
	v_cndmask_b32_e32 v8, v246, v74, vcc
	v_cmp_le_i32_e32 vcc, v163, v199
	s_nop 1
	v_cndmask_b32_e32 v9, v246, v75, vcc
	v_cmp_le_i32_e32 vcc, v164, v199
	v_max3_f32 v12, v10, v8, v9
	s_nop 0
	v_cndmask_b32_e32 v10, v246, v76, vcc
	v_cmp_le_i32_e32 vcc, v165, v199
	s_nop 1
	v_cndmask_b32_e32 v11, v246, v77, vcc
	v_cmp_le_i32_e32 vcc, v166, v199
	v_max3_f32 v14, v12, v10, v11
	s_nop 0
	v_cndmask_b32_e32 v12, v246, v122, vcc
	v_cmp_le_i32_e32 vcc, v167, v199
	s_nop 1
	v_cndmask_b32_e32 v13, v246, v123, vcc
	v_cmp_le_i32_e32 vcc, v168, v199
	v_max3_f32 v200, v14, v12, v13
	s_nop 0
	v_cndmask_b32_e32 v14, v246, v124, vcc
	v_cmp_le_i32_e32 vcc, v169, v199
	s_nop 1
	v_cndmask_b32_e32 v15, v246, v125, vcc
	v_max3_f32 v200, v200, v14, v15
	s_cbranch_execnz .LBB0_1266

.LBB0_1267:
	s_and_b32 s25, s25, s23
	s_cmp_lg_u32 s25, 0
	s_cselect_b64 s[42:43], -1, 0
	s_cmp_eq_u32 s25, 0
	s_cbranch_scc1 .LBB0_1272
	s_waitcnt lgkmcnt(7)
	v_mfma_f32_16x16x32_bf16 v[0:3], v[98:101], v[30:33], 0
	v_cndmask_b32_e64 v4, v41, v40, s[4:5]
	v_cndmask_b32_e64 v4, v4, v39, s[6:7]
	v_cndmask_b32_e64 v4, v4, v38, s[8:9]
	s_waitcnt lgkmcnt(5)
	v_mfma_f32_16x16x32_bf16 v[98:101], v[118:121], v[34:37], v[0:3]
	v_and_b32_e32 v4, s23, v4
	s_lshl_b32 s4, s21, 6
	v_subrev_u32_e32 v5, s4, v171
	v_mfma_f32_16x16x32_bf16 v[0:3], v[102:105], v[30:33], 0
	v_cmp_ne_u32_e32 vcc, 0, v4
	s_waitcnt lgkmcnt(4)
	v_mfma_f32_16x16x32_bf16 v[86:89], v[110:113], v[34:37], v[0:3]
	s_waitcnt lgkmcnt(3)
	v_mfma_f32_16x16x32_bf16 v[0:3], v[114:117], v[30:33], 0
	s_waitcnt lgkmcnt(1)
	v_mfma_f32_16x16x32_bf16 v[78:81], v[106:109], v[34:37], v[0:3]
	v_mfma_f32_16x16x32_bf16 v[0:3], v[94:97], v[30:33], 0
	v_cndmask_b32_e32 v94, -1, v5, vcc
	v_cmp_gt_u32_e32 vcc, 63, v94
	s_waitcnt lgkmcnt(0)
	v_mfma_f32_16x16x32_bf16 v[90:93], v[90:93], v[34:37], v[0:3]
	s_cbranch_vccz .LBB0_1278
	v_cmp_le_i32_e32 vcc, v153, v94
	s_nop 2
	v_cndmask_b32_e32 v0, v246, v98, vcc
	v_cmp_lt_i32_e32 vcc, v153, v94
	s_nop 1
	v_cndmask_b32_e32 v1, v246, v99, vcc
	v_cmp_le_i32_e32 vcc, v155, v94
	v_max3_f32 v4, v0, s96, v1
	s_nop 0
	v_cndmask_b32_e32 v2, v246, v100, vcc
	v_cmp_le_i32_e32 vcc, v156, v94
	s_nop 1
	v_cndmask_b32_e32 v3, v246, v101, vcc
	v_cmp_le_i32_e32 vcc, v158, v94
	v_max3_f32 v6, v4, v2, v3
	s_nop 0
	v_cndmask_b32_e32 v4, v246, v86, vcc
	v_cmp_le_i32_e32 vcc, v159, v94
	s_nop 1
	v_cndmask_b32_e32 v5, v246, v87, vcc
	v_cmp_le_i32_e32 vcc, v160, v94
	v_max3_f32 v8, v6, v4, v5
	s_nop 0
	v_cndmask_b32_e32 v6, v246, v88, vcc
	v_cmp_le_i32_e32 vcc, v161, v94
	s_nop 1
	v_cndmask_b32_e32 v7, v246, v89, vcc
	v_cmp_le_i32_e32 vcc, v162, v94
	v_max3_f32 v10, v8, v6, v7
	s_nop 0
	v_cndmask_b32_e32 v8, v246, v78, vcc
	v_cmp_le_i32_e32 vcc, v163, v94
	s_nop 1
	v_cndmask_b32_e32 v9, v246, v79, vcc
	v_cmp_le_i32_e32 vcc, v164, v94
	v_max3_f32 v12, v10, v8, v9
	s_nop 0
	v_cndmask_b32_e32 v10, v246, v80, vcc
	v_cmp_le_i32_e32 vcc, v165, v94
	s_nop 1
	v_cndmask_b32_e32 v11, v246, v81, vcc
	v_cmp_le_i32_e32 vcc, v166, v94
	v_max3_f32 v14, v12, v10, v11
	s_nop 0
	v_cndmask_b32_e32 v12, v246, v90, vcc
	v_cmp_le_i32_e32 vcc, v167, v94
	s_nop 1
	v_cndmask_b32_e32 v13, v246, v91, vcc
	v_cmp_le_i32_e32 vcc, v168, v94
	v_max3_f32 v95, v14, v12, v13
	s_nop 0
	v_cndmask_b32_e32 v14, v246, v92, vcc
	v_cmp_le_i32_e32 vcc, v169, v94
	s_nop 1
	v_cndmask_b32_e32 v15, v246, v93, vcc
	v_max3_f32 v95, v95, v14, v15
	s_cbranch_execnz .LBB0_1271
